# in-proj third round: idle workgroups convert 2 weight chunks instead of 1 (moves conversion out of the attention tail)
# speedup vs baseline: 1.0092x; 1.0046x over previous
; #define LAS __attribute__((address_space(3)))
; __device__ __forceinline__ void tr_drain(ArgsP a, LAS unsigned char* lds, int tid, int* counter, int l, int late, int max_chunks) {
;     LAS int* slot = (LAS int*)(lds + LDS_BYTES - 64);
;     const int lane = tid & 63, wave = __builtin_amdgcn_readfirstlane(tid >> 6), n_items = late ? TR_N_LATE : TR_N_EARLY, n_chunks = (n_items + TR_CHUNK - 1) / TR_CHUNK;
;     LAS float* scr = (LAS float*)(lds + wave * 8704);
;     for (int n = 0; n < max_chunks; ++n) {
;         if (tid == 0) *slot = atomicAdd(counter, 1);
;         __syncthreads();
;         const int ch = *slot;
;         __syncthreads();
;         if (ch >= n_chunks) break;
; #pragma unroll 1
;         for (int j = 0; j < 4; ++j) { const int i = ch * TR_CHUNK + wave * 4 + j; if (i < n_items) tr_dispatch(a, l, late ? tr_late_item(i) : tr_early_item(i), scr, lane); }
;     }
; }
; __global__ void __launch_bounds__(512, 2) fwd_kernel(Args a_unused) {
;     ...
;             if ((int)blockIdx.x >= (SEQ / 256) * (NINP / 256) - 2 * G) tr_drain(a, lds, tid_, (int*)(ws + WS_CNT) + 24 + 2 * l, l, 1, 1);
.LBB0_1457:
	s_mov_b32 s100, 0
	v_readlane_b32 s4, v254, 23
	v_readlane_b32 s5, v254, 24
	s_andn2_b64 vcc, exec, s[4:5]
	s_cbranch_vccnz .LBB0_1582
.Ldrain_again:
	v_readfirstlane_b32 s2, v227
	v_cmp_eq_u32_e32 vcc, 0, v227
	s_and_saveexec_b64 s[4:5], vcc
	s_cbranch_execz .LBB0_1462
	s_mov_b64 s[8:9], exec
	v_mbcnt_lo_u32_b32 v0, s8, 0
	v_mbcnt_hi_u32_b32 v0, s9, v0
	v_cmp_eq_u32_e32 vcc, 0, v0
	s_and_saveexec_b64 s[6:7], vcc
	s_cbranch_execz .LBB0_1461
	s_lshl_b32 s10, s64, 1
	s_ashr_i32 s11, s10, 31
	s_lshl_b64 s[10:11], s[10:11], 2
	s_add_u32 s10, s66, s10
	s_addc_u32 s11, s67, s11
	s_bcnt1_i32_b64 s8, s[8:9]
	v_mov_b32_e32 v2, s8
	global_atomic_add v2, v1, v2, s[10:11] offset:96 sc0

; __device__ __forceinline__ void tr_drain(ArgsP a, LAS unsigned char* lds, int tid, int* counter, int l, int late, int max_chunks) {
;     ...
;     for (int n = 0; n < max_chunks; ++n) {
;         if (tid == 0) *slot = atomicAdd(counter, 1);
;         __syncthreads();
;         const int ch = *slot;
;         __syncthreads();
;         if (ch >= n_chunks) break;
; #pragma unroll 1
;         for (int j = 0; j < 4; ++j) { const int i = ch * TR_CHUNK + wave * 4 + j; if (i < n_items) tr_dispatch(a, l, late ? tr_late_item(i) : tr_early_item(i), scr, lane); }
;     }
; }
; __global__ void __launch_bounds__(512, 2) fwd_kernel(Args a_unused) {
;     ...
;             if ((int)blockIdx.x >= (SEQ / 256) * (NINP / 256) - 2 * G) tr_drain(a, lds, tid_, (int*)(ws + WS_CNT) + 24 + 2 * l, l, 1, 1);
.Ldrain_more:
	s_add_i32 s100, s100, 1
	s_cmp_ge_u32 s100, 2
	s_cbranch_scc1 .LBB0_1582
	s_mul_i32 s14, s64, 0x1300000
	s_mul_hi_i32 s15, s64, 0x1300000
	s_add_u32 s14, s66, s14
	s_addc_u32 s15, s67, s15
	s_add_u32 s14, s14, 0x400000
	s_addc_u32 s15, s15, 0
	s_branch .Ldrain_again
